# P4a chunk-operator stages S3/S7/S9: LDS operand reads renamed into free VGPRs and hoisted to the top of each stage, counted lgkmcnt waits at first use
# baseline (speedup 1.0000x reference)
; __device__ __forceinline__ unsigned pk2(float lo, float hi) { f32x2_t v = {lo, hi}; bf16x2_t b = __builtin_convertvector(v, bf16x2_t); return __builtin_bit_cast(unsigned, b); }
; #define LBAR() do { asm volatile("s_waitcnt lgkmcnt(0)" ::: "memory"); __builtin_amdgcn_s_barrier(); asm volatile("" ::: "memory"); } while (0)
; __device__ __forceinline__ f32x4 bf4(u32x2 w) { return (f32x4){__uint_as_float(w.x << 16), __uint_as_float(w.x & 0xffff0000u), __uint_as_float(w.y << 16), __uint_as_float(w.y & 0xffff0000u)}; }
; __device__ __forceinline__ void chunk_item(const PAArgs& A, unsigned char* lds, int item, int tid, int wave, int lane, const ChunkRaw& RAW) {
;     ...
;     {
;         typedef short s16x4 __attribute__((ext_vector_type(4)));
;         const int cb = (wave & 3) * 16 + fr;
;         const bf16* src = (wave < 4 ? ATT : AVT) + cb * MST;
;         bf16* dst = (wave < 4 ? X1T : ZT) + cb * MST;
;         s16x4 xb[4];
; #pragma unroll
;         for (int bi = 0; bi < 4; ++bi) {
;             f32x4 acc = bf4(*(const u32x2*)(src + bi * 16 + fq * 4));
; #pragma unroll
;             for (int bj = 0; bj < bi; ++bj) acc = __builtin_amdgcn_mfma_f32_16x16x16bf16_1k(*(const s16x4*)(AABb + (bi * 16 + fr) * MST + bj * 16 + fq * 4), xb[bj], acc, 0, 0, 0);
;             const u32x2 tb = (u32x2){pk2(acc[0], acc[1]), pk2(acc[2], acc[3])};
;             const f32x4 xv = __builtin_amdgcn_mfma_f32_16x16x16bf16_1k(*(const s16x4*)(Tinv + (bi * 16 + fr) * TST + fq * 4), __builtin_bit_cast(s16x4, tb), z4, 0, 0, 0);
;             const u32x2 xw = (u32x2){pk2(xv[0], xv[1]), pk2(xv[2], xv[3])};
;             xb[bi] = __builtin_bit_cast(s16x4, xw);
;             *(u32x2*)(dst + bi * 16 + fq * 4) = xw;
;         }
;     }
;     LBAR();
.LBB0_428:
	s_waitcnt lgkmcnt(0)
	s_barrier
	ds_read_b64 v[140:141], v75
	ds_read_b64 v[142:143], v97
	ds_read_b64 v[144:145], v98
	ds_read_b64 v[146:147], v75 offset:32
	ds_read_b64 v[148:149], v97 offset:640
	ds_read_b64 v[154:155], v75 offset:64
	ds_read_b64 v[156:157], v97 offset:1280
	ds_read_b64 v[158:159], v75 offset:96
	ds_read_b64 v[160:161], v97 offset:1920
	s_nop 0
	v_add_u32_e32 v18, 0x800, v98
	ds_read2_b64 v[150:153], v18 offset0:32 offset1:36
	s_mov_b32 s6, 0x6000000
	s_nop 0
	s_waitcnt lgkmcnt(9)
	v_lshlrev_b32_e32 v2, 16, v140
	v_and_b32_e32 v0, 0xffff0000, v140
	v_lshlrev_b32_e32 v3, 16, v141
	v_and_b32_e32 v1, 0xffff0000, v141
	v_cvt_pk_bf16_f32 v0, v2, v0
	v_cvt_pk_bf16_f32 v1, v3, v1
	s_nop 0
	s_nop 0
	s_waitcnt lgkmcnt(8)
	v_mfma_f32_16x16x16_bf16 v[0:3], v[142:143], v[0:1], 0
	s_nop 7
	v_cvt_pk_bf16_f32 v0, v0, v1
	v_cvt_pk_bf16_f32 v1, v2, v3
	ds_write_b64 v76, v[0:1]
	s_nop 0
	s_nop 0
	s_nop 0
	s_waitcnt lgkmcnt(7)
	v_lshlrev_b32_e32 v2, 16, v146
	v_and_b32_e32 v3, 0xffff0000, v146
	v_lshlrev_b32_e32 v4, 16, v147
	v_and_b32_e32 v5, 0xffff0000, v147
	s_nop 1
	v_mfma_f32_16x16x16_bf16 v[2:5], v[144:145], v[0:1], v[2:5]
	s_nop 7
	v_cvt_pk_bf16_f32 v2, v2, v3
	v_cvt_pk_bf16_f32 v3, v4, v5
	s_nop 0
	s_nop 0
	s_waitcnt lgkmcnt(6)
	v_mfma_f32_16x16x16_bf16 v[2:5], v[148:149], v[2:3], 0
	s_nop 7
	v_cvt_pk_bf16_f32 v6, v2, v3
	v_cvt_pk_bf16_f32 v7, v4, v5
	ds_write_b64 v76, v[6:7] offset:32
	s_nop 0
	s_nop 0
	s_nop 0
	s_waitcnt lgkmcnt(6)
	v_lshlrev_b32_e32 v2, 16, v154
	v_and_b32_e32 v3, 0xffff0000, v154
	v_lshlrev_b32_e32 v4, 16, v155
	v_and_b32_e32 v5, 0xffff0000, v155
	s_nop 1
	s_waitcnt lgkmcnt(2)
	v_mfma_f32_16x16x16_bf16 v[2:5], v[150:151], v[0:1], v[2:5]
	v_add_u32_e32 v18, 0x1000, v98
	v_mfma_f32_16x16x16_bf16 v[2:5], v[152:153], v[6:7], v[2:5]
	s_nop 7
	v_cvt_pk_bf16_f32 v2, v2, v3
	v_cvt_pk_bf16_f32 v3, v4, v5
	s_nop 0
	s_nop 0
	v_mfma_f32_16x16x16_bf16 v[2:5], v[156:157], v[2:3], 0
	s_nop 7
	v_cvt_pk_bf16_f32 v116, v2, v3
	v_cvt_pk_bf16_f32 v117, v4, v5
	ds_write_b64 v76, v[116:117] offset:64
	ds_read2_b64 v[18:21], v18 offset0:64 offset1:68
	s_nop 0
	s_nop 0
	v_lshlrev_b32_e32 v2, 16, v158
	v_and_b32_e32 v3, 0xffff0000, v158
	v_lshlrev_b32_e32 v4, 16, v159
	v_and_b32_e32 v5, 0xffff0000, v159
	s_nop 1
	s_waitcnt lgkmcnt(0)
	v_mfma_f32_16x16x16_bf16 v[0:3], v[18:19], v[0:1], v[2:5]
	s_nop 2
	ds_read_b64 v[4:5], v98 offset:4672
	v_mfma_f32_16x16x16_bf16 v[0:3], v[20:21], v[6:7], v[0:3]
	s_nop 0
	s_waitcnt lgkmcnt(0)
	v_mfma_f32_16x16x16_bf16 v[0:3], v[4:5], v[116:117], v[0:3]
	s_nop 7
	v_cvt_pk_bf16_f32 v0, v0, v1
	v_cvt_pk_bf16_f32 v1, v2, v3
	s_nop 0
	s_nop 0
	v_mfma_f32_16x16x16_bf16 v[0:3], v[160:161], v[0:1], 0
	s_nop 7
	v_cvt_pk_bf16_f32 v0, v0, v1
	v_cvt_pk_bf16_f32 v1, v2, v3
	ds_write_b64 v76, v[0:1] offset:96
	s_waitcnt lgkmcnt(0)
	s_waitcnt lgkmcnt(0)
	s_barrier
; __device__ __forceinline__ unsigned pk2(float lo, float hi) { f32x2_t v = {lo, hi}; bf16x2_t b = __builtin_convertvector(v, bf16x2_t); return __builtin_bit_cast(unsigned, b); }
; __device__ __forceinline__ void chunk_item(const PAArgs& A, unsigned char* lds, int item, int tid, int wave, int lane, const ChunkRaw& RAW) {
;     ...
;     {
;         f32x4 c0, c1;
;         const int fl = lane * 4;
;         { const u32x2 w0 = *(const u32x2*)(RT + (tj0 * 16 + fr) * MST + ti * 16 + fq * 4), w1 = *(const u32x2*)(RT + (tj0 * 16 + 16 + fr) * MST + ti * 16 + fq * 4);
;           c0 = (f32x4){__uint_as_float(w0.x << 16), __uint_as_float(w0.x & 0xffff0000u), __uint_as_float(w0.y << 16), __uint_as_float(w0.y & 0xffff0000u)};
;           c1 = (f32x4){__uint_as_float(w1.x << 16), __uint_as_float(w1.x & 0xffff0000u), __uint_as_float(w1.y << 16), __uint_as_float(w1.y & 0xffff0000u)}; }
;         mm2(X1T, ARB, ti, tj0, fr, fq, c0, c1);
;         const int fpos = (((ti >> 1) * 64) + ((ti & 1) * 2 + (fq >> 1)) * 16 + fr) * 8 + (fq & 1) * 4;
;         *(u32x2*)(RPg + tj0 * 1024 + fpos) = (u32x2){pk2(c0[0], c0[1]), pk2(c0[2], c0[3])};
;         *(u32x2*)(RPg + (tj0 + 1) * 1024 + fpos) = (u32x2){pk2(c1[0], c1[1]), pk2(c1[2], c1[3])};
;         c0 = z4; c1 = z4; mm2(ZT, ARB, ti, tj0, fr, fq, c0, c1); mm2(VT, ARK, ti, tj0, fr, fq, c0, c1);
;         *(u32x2*)(Y0g + (ti * 4 + tj0) * 256 + fl) = (u32x2){pk2(c0[0], c0[1]), pk2(c0[2], c0[3])};
;         *(u32x2*)(Y0g + (ti * 4 + tj0 + 1) * 256 + fl) = (u32x2){pk2(c1[0], c1[1]), pk2(c1[2], c1[3])};
;         c0 = z4; c1 = z4; mm2(X1T, BHT, ti, tj0, fr, fq, c0, c1);
;         { const int chp = ti * 16 + fq * 4, cha = tj0 * 16 + fr, chb = cha + 16; const float wa = WCs[cha], wb = WCs[chb];
; #pragma unroll
;           for (int r = 0; r < 4; ++r) { c0[r] += (chp + r == cha) ? wa : 0.f; c1[r] += (chp + r == chb) ? wb : 0.f; }
;           *(u32x2*)(Pg + tj0 * 1024 + fpos) = (u32x2){pk2(c0[0], c0[1]), pk2(c0[2], c0[3])};
;           *(u32x2*)(Pg + (tj0 + 1) * 1024 + fpos) = (u32x2){pk2(c1[0], c1[1]), pk2(c1[2], c1[3])}; }
;         c0 = z4; c1 = z4; mm2(BHT, ZT, ti, tj0, fr, fq, c0, c1); mm2(KHT, VT, ti, tj0, fr, fq, c0, c1);
;         *(f32x4*)(Qg + (ti * 4 + tj0) * 256 + fl) = c0;
;         *(f32x4*)(Qg + (ti * 4 + tj0 + 1) * 256 + fl) = c1;
;     }
	ds_read_b64 v[156:157], v79 offset:27648
	ds_read_b64 v[158:159], v79 offset:29952
	ds_read_b128 v[160:163], v80
	ds_read_b128 v[164:167], v88
	ds_read_b128 v[168:171], v89
	ds_read_b128 v[172:175], v80 offset:64
	ds_read_b128 v[176:179], v88 offset:64
	ds_read_b128 v[180:183], v90
	ds_read_b128 v[184:187], v90 offset:64
	ds_read_b128 v[188:191], v52 offset:55296
	ds_read_b128 v[192:195], v91
	ds_read_b128 v[196:199], v92
	ds_read_b128 v[200:203], v52 offset:55360
	ds_read_b128 v[204:207], v53 offset:36864
	ds_read_b128 v[208:211], v53 offset:39168
	s_waitcnt lgkmcnt(14)
	ds_read_b128 v[212:215], v53 offset:36928
	s_waitcnt lgkmcnt(14)
	ds_read_b128 v[216:219], v53 offset:39232
	s_waitcnt lgkmcnt(14)
	ds_read_b32 v220, v81
	s_waitcnt lgkmcnt(14)
	ds_read_b128 v[222:225], v52 offset:36864
	s_waitcnt lgkmcnt(14)
	ds_read_b128 v[226:229], v93
	s_waitcnt lgkmcnt(14)
	ds_read_b128 v[230:233], v94
	s_waitcnt lgkmcnt(14)
	ds_read_b128 v[234:237], v52 offset:36928
	s_nop 0
	s_nop 0
	s_nop 0
	v_lshlrev_b32_e32 v0, 16, v156
	s_nop 0
	v_lshlrev_b32_e32 v18, 16, v158
	v_and_b32_e32 v19, 0xffff0000, v158
	v_lshlrev_b32_e32 v20, 16, v159
	v_and_b32_e32 v21, 0xffff0000, v159
	s_nop 0
	s_nop 0
	s_nop 0
	v_and_b32_e32 v1, 0xffff0000, v156
	v_lshlrev_b32_e32 v2, 16, v157
	v_and_b32_e32 v3, 0xffff0000, v157
	s_nop 0
	v_mfma_f32_16x16x32_bf16 v[18:21], v[160:163], v[168:171], v[18:21]
	v_mfma_f32_16x16x32_bf16 v[124:127], v[160:163], v[164:167], v[0:3]
	s_nop 2
	s_nop 0
	s_nop 0
	s_waitcnt lgkmcnt(14)
	ds_read_b128 v[132:135], v89 offset:64
	s_nop 0
	v_mfma_f32_16x16x32_bf16 v[124:127], v[172:175], v[176:179], v[124:127]
	s_nop 0
	s_waitcnt lgkmcnt(0)
	v_mfma_f32_16x16x32_bf16 v[18:21], v[172:175], v[132:135], v[18:21]
	s_nop 5
	v_cvt_pk_bf16_f32 v124, v124, v125
	v_cvt_pk_bf16_f32 v125, v126, v127
	v_lshl_add_u64 v[126:127], v[16:17], 0, s[50:51]
	v_add_co_u32_e32 v126, vcc, s6, v126
	s_brev_b32 s6, 32
	s_nop 0
	v_addc_co_u32_e32 v127, vcc, 0, v127, vcc
	v_cvt_pk_bf16_f32 v18, v18, v19
	v_cvt_pk_bf16_f32 v19, v20, v21
	global_store_dwordx2 v[126:127], v[18:19], off offset:2048
	s_nop 0
	s_nop 0
	v_mfma_f32_16x16x32_bf16 v[116:119], v[180:183], v[164:167], 0
	global_store_dwordx2 v[126:127], v[124:125], off
	v_lshl_add_u64 v[16:17], v[16:17], 0, s[52:53]
	v_mfma_f32_16x16x32_bf16 v[18:21], v[180:183], v[168:171], 0
	s_nop 0
	s_nop 0
	v_mfma_f32_16x16x32_bf16 v[116:119], v[184:187], v[176:179], v[116:119]
	v_mfma_f32_16x16x32_bf16 v[18:21], v[184:187], v[132:135], v[18:21]
	s_nop 0
	s_nop 0
	s_nop 0
	s_nop 0
	v_mfma_f32_16x16x32_bf16 v[116:119], v[188:191], v[192:195], v[116:119]
	s_nop 0
	v_mfma_f32_16x16x32_bf16 v[18:21], v[188:191], v[196:199], v[18:21]
	s_nop 0
	ds_read_b128 v[124:127], v91 offset:64
	ds_read_b128 v[128:131], v92 offset:64
	s_nop 0
	s_waitcnt lgkmcnt(1)
	v_mfma_f32_16x16x32_bf16 v[116:119], v[200:203], v[124:127], v[116:119]
	v_perm_b32 v126, v106, v104, s37
	v_perm_b32 v127, v105, v103, s37
	s_nop 0
	s_waitcnt lgkmcnt(0)
	v_mfma_f32_16x16x32_bf16 v[18:21], v[200:203], v[128:131], v[18:21]
	s_nop 3
	v_cvt_pk_bf16_f32 v116, v116, v117
	v_cvt_pk_bf16_f32 v117, v118, v119
	v_lshl_add_u64 v[118:119], v[14:15], 0, s[50:51]
	v_add_co_u32_e32 v118, vcc, s6, v118
	s_mov_b32 s6, 0x1b800000
	s_nop 0
	v_addc_co_u32_e32 v119, vcc, 0, v119, vcc
	v_cvt_pk_bf16_f32 v18, v18, v19
	v_cvt_pk_bf16_f32 v19, v20, v21
	global_store_dwordx2 v[118:119], v[116:117], off
	global_store_dwordx2 v[118:119], v[18:19], off offset:512
	s_nop 0
	s_nop 0
	s_nop 0
	v_mfma_f32_16x16x32_bf16 v[18:21], v[160:163], v[204:207], 0
	v_lshl_add_u64 v[14:15], v[14:15], 0, s[52:53]
	s_nop 0
	v_mfma_f32_16x16x32_bf16 v[4:7], v[160:163], v[208:211], 0
	s_nop 0
	s_nop 0
	s_nop 0
	v_mfma_f32_16x16x32_bf16 v[18:21], v[172:175], v[212:215], v[18:21]
	s_nop 0
	v_mfma_f32_16x16x32_bf16 v[0:3], v[172:175], v[216:219], v[4:7]
	s_nop 2
	s_nop 0
	ds_read_b32 v115, v82
	s_nop 0
	v_cndmask_b32_e64 v4, 0, v220, s[84:85]
	v_add_f32_e32 v18, v18, v4
	v_cndmask_b32_e64 v4, 0, v220, s[86:87]
	v_add_f32_e32 v19, v19, v4
	s_nop 0
	s_waitcnt lgkmcnt(0)
	v_cndmask_b32_e64 v5, 0, v115, s[90:91]
	v_cndmask_b32_e64 v4, 0, v115, s[88:89]
	v_pk_add_f32 v[0:1], v[0:1], v[4:5]
	v_cndmask_b32_e64 v5, 0, v220, s[92:93]
	v_cndmask_b32_e64 v4, 0, v220, s[94:95]
	v_pk_add_f32 v[4:5], v[20:21], v[4:5]
	v_cndmask_b32_e64 v7, 0, v115, s[96:97]
	v_cndmask_b32_e64 v6, 0, v115, s[18:19]
	v_pk_add_f32 v[2:3], v[2:3], v[6:7]
	v_cvt_pk_bf16_f32 v7, v4, v5
	v_lshl_add_u64 v[4:5], v[12:13], 0, s[50:51]
	v_add_co_u32_e32 v4, vcc, s6, v4
	v_cvt_pk_bf16_f32 v6, v18, v19
	s_nop 0
	v_addc_co_u32_e32 v5, vcc, 0, v5, vcc
	v_cvt_pk_bf16_f32 v0, v0, v1
	v_cvt_pk_bf16_f32 v1, v2, v3
	global_store_dwordx2 v[4:5], v[6:7], off
	global_store_dwordx2 v[4:5], v[0:1], off offset:2048
	s_nop 0
	s_nop 0
	s_nop 0
	s_nop 0
	v_mfma_f32_16x16x32_bf16 v[4:7], v[222:225], v[226:229], 0
	v_lshl_add_u64 v[12:13], v[12:13], 0, s[52:53]
	s_and_b64 vcc, exec, s[40:41]
	s_nop 0
	v_mfma_f32_16x16x32_bf16 v[0:3], v[222:225], v[230:233], 0
	s_nop 0
	ds_read_b128 v[116:119], v93 offset:64
	ds_read_b128 v[120:123], v94 offset:64
	s_nop 0
	s_waitcnt lgkmcnt(1)
	v_mfma_f32_16x16x32_bf16 v[4:7], v[234:237], v[116:119], v[4:7]
	s_nop 0
	s_waitcnt lgkmcnt(0)
	v_mfma_f32_16x16x32_bf16 v[0:3], v[234:237], v[120:123], v[0:3]
	ds_read_b128 v[18:21], v52 offset:46080
	ds_read_b128 v[116:119], v53 offset:55296
	ds_read_b128 v[120:123], v53 offset:57600
	s_nop 0
	s_waitcnt lgkmcnt(1)
	v_mfma_f32_16x16x32_bf16 v[4:7], v[18:21], v[116:119], v[4:7]
	s_nop 0
	s_waitcnt lgkmcnt(0)
	v_mfma_f32_16x16x32_bf16 v[0:3], v[18:21], v[120:123], v[0:3]
	ds_read_b128 v[18:21], v52 offset:46144
	ds_read_b128 v[116:119], v53 offset:55360
	ds_read_b128 v[120:123], v53 offset:57664
	s_nop 0
	s_waitcnt lgkmcnt(1)
	v_mfma_f32_16x16x32_bf16 v[4:7], v[18:21], v[116:119], v[4:7]
	s_nop 0
	s_waitcnt lgkmcnt(0)
	v_mfma_f32_16x16x32_bf16 v[0:3], v[18:21], v[120:123], v[0:3]
	s_nop 5
	global_store_dwordx4 v[10:11], v[4:7], off offset:-1024
	s_nop 0
	global_store_dwordx4 v[10:11], v[0:3], off
	s_nop 1
	v_perm_b32 v3, v114, v112, s37
	v_perm_b32 v5, v113, v111, s37
	v_perm_b32 v122, v110, v108, s37
	v_perm_b32 v123, v109, v107, s37
	v_perm_b32 v6, v102, v100, s37
	v_perm_b32 v7, v101, v99, s37
	v_lshl_add_u64 v[10:11], v[10:11], 0, s[24:25]
	s_waitcnt lgkmcnt(0)
	s_cbranch_vccnz .LBB0_437

; __device__ __forceinline__ unsigned pk2(float lo, float hi) { f32x2_t v = {lo, hi}; bf16x2_t b = __builtin_convertvector(v, bf16x2_t); return __builtin_bit_cast(unsigned, b); }
; #define LBAR() do { asm volatile("s_waitcnt lgkmcnt(0)" ::: "memory"); __builtin_amdgcn_s_barrier(); asm volatile("" ::: "memory"); } while (0)
; __device__ __forceinline__ void chunk_item(const PAArgs& A, unsigned char* lds, int item, int tid, int wave, int lane, const ChunkRaw& RAW) {
;     ...
;         c0 = z4; c1 = z4; mm2(KT, AT, ti, tj0, fr, fq, c0, c1);
;         { const f32x4 m0 = S3_MASK(c0, ta, 0), m1 = S3_MASK(c1, tb, 0);
;           *(u32x2*)(AAK + ta * MST + jb) = (u32x2){pk2(m0[0], m0[1]), pk2(m0[2], m0[3])}; *(u32x2*)(AAK + tb * MST + jb) = (u32x2){pk2(m1[0], m1[1]), pk2(m1[2], m1[3])}; }
;         c0 = z4; c1 = z4; mm2(BT, RT, ti, tj0, fr, fq, c0, c1);
;         { const f32x4 m0 = S3_MASK(c0, ta, 1), m1 = S3_MASK(c1, tb, 1);
;           *(u32x2*)(ARB + ta * MST + jb) = (u32x2){pk2(m0[0], m0[1]), pk2(m0[2], m0[3])}; *(u32x2*)(ARB + tb * MST + jb) = (u32x2){pk2(m1[0], m1[1]), pk2(m1[2], m1[3])}; }
;         c0 = z4; c1 = z4; mm2(KT, RT, ti, tj0, fr, fq, c0, c1);
;         { const f32x4 m0 = S3_MASK(c0, ta, 1), m1 = S3_MASK(c1, tb, 1);
;           *(u32x2*)(ARK + ta * MST + jb) = (u32x2){pk2(m0[0], m0[1]), pk2(m0[2], m0[3])}; *(u32x2*)(ARK + tb * MST + jb) = (u32x2){pk2(m1[0], m1[1]), pk2(m1[2], m1[3])}; }
;     ...
;     }
;     LBAR();
;     {
;         f32x4 c0 = z4, c1 = z4;
;         mm2(AAK, VT, ti, tj0, fr, fq, c0, c1);
;         *(u32x2*)(AVT + (tj0 * 16 + fr) * MST + ti * 16 + fq * 4) = (u32x2){pk2(c0[0], c0[1]), pk2(c0[2], c0[3])};
;         *(u32x2*)(AVT + (tj0 * 16 + 16 + fr) * MST + ti * 16 + fq * 4) = (u32x2){pk2(c1[0], c1[1]), pk2(c1[2], c1[3])};
.LBB0_435:
	ds_read_b128 v[120:123], v52 offset:18432
	ds_read_b128 v[124:127], v53
	ds_read_b128 v[128:131], v53 offset:2304
	ds_read_b128 v[132:135], v52 offset:18496
	ds_read_b128 v[136:139], v53 offset:64
	ds_read_b128 v[140:143], v53 offset:2368
	ds_read_b128 v[144:147], v52 offset:9216
	ds_read_b128 v[148:151], v53 offset:27648
	ds_read_b128 v[152:155], v53 offset:29952
	ds_read_b128 v[156:159], v52 offset:9280
	ds_read_b128 v[160:163], v53 offset:27712
	ds_read_b128 v[164:167], v53 offset:30016
	ds_read_b128 v[168:171], v52 offset:18432
	ds_read_b128 v[172:175], v53 offset:27648
	ds_read_b128 v[176:179], v53 offset:29952
	s_waitcnt lgkmcnt(14)
	ds_read_b128 v[180:183], v53 offset:27712
	s_nop 0
	s_nop 0
	s_nop 0
	s_nop 0
	s_and_b64 vcc, exec, s[6:7]
	s_nop 0
	s_waitcnt lgkmcnt(14)
	v_mfma_f32_16x16x32_bf16 v[4:7], v[120:123], v[124:127], 0
	s_nop 0
	s_waitcnt lgkmcnt(13)
	v_mfma_f32_16x16x32_bf16 v[0:3], v[120:123], v[128:131], 0
	s_nop 0
	s_nop 0
	s_waitcnt lgkmcnt(11)
	v_mfma_f32_16x16x32_bf16 v[4:7], v[132:135], v[136:139], v[4:7]
	s_nop 0
	s_nop 0
	s_waitcnt lgkmcnt(10)
	v_mfma_f32_16x16x32_bf16 v[0:3], v[132:135], v[140:143], v[0:3]
	s_nop 4
	v_cndmask_b32_e64 v4, 0, v4, s[54:55]
	v_cndmask_b32_e64 v5, 0, v5, s[22:23]
	v_cndmask_b32_e64 v6, 0, v6, s[20:21]
	v_cndmask_b32_e64 v7, 0, v7, s[56:57]
	v_cndmask_b32_e64 v18, 0, v0, s[58:59]
	v_cndmask_b32_e64 v19, 0, v1, s[60:61]
	v_cndmask_b32_e64 v2, 0, v2, s[62:63]
	v_cndmask_b32_e64 v3, 0, v3, s[64:65]
	v_cvt_pk_bf16_f32 v0, v4, v5
	v_cvt_pk_bf16_f32 v1, v6, v7
	ds_write_b64 v77, v[0:1] offset:64512
	v_cvt_pk_bf16_f32 v0, v18, v19
	v_cvt_pk_bf16_f32 v1, v2, v3
	ds_write_b64 v78, v[0:1] offset:64512
	s_nop 0
	s_nop 0
	s_nop 0
	s_nop 0
	s_nop 0
	s_waitcnt lgkmcnt(10)
	v_mfma_f32_16x16x32_bf16 v[4:7], v[144:147], v[148:151], 0
	s_nop 0
	s_waitcnt lgkmcnt(9)
	v_mfma_f32_16x16x32_bf16 v[0:3], v[144:147], v[152:155], 0
	s_nop 0
	s_nop 0
	s_waitcnt lgkmcnt(7)
	v_mfma_f32_16x16x32_bf16 v[4:7], v[156:159], v[160:163], v[4:7]
	s_nop 0
	s_nop 0
	s_waitcnt lgkmcnt(6)
	v_mfma_f32_16x16x32_bf16 v[0:3], v[156:159], v[164:167], v[0:3]
	s_nop 4
	v_cndmask_b32_e64 v4, v4, 0, s[66:67]
	v_cndmask_b32_e64 v5, 0, v5, s[54:55]
	v_cndmask_b32_e64 v6, v6, 0, s[72:73]
	v_cndmask_b32_e64 v7, v7, 0, s[16:17]
	v_cndmask_b32_e64 v18, 0, v0, s[76:77]
	v_cndmask_b32_e64 v19, 0, v1, s[78:79]
	v_cndmask_b32_e64 v2, 0, v2, s[80:81]
	v_cndmask_b32_e64 v3, 0, v3, s[82:83]
	v_cvt_pk_bf16_f32 v0, v4, v5
	v_cvt_pk_bf16_f32 v1, v6, v7
	ds_write_b64 v83, v[0:1]
	v_cvt_pk_bf16_f32 v0, v18, v19
	v_cvt_pk_bf16_f32 v1, v2, v3
	ds_write_b64 v84, v[0:1]
	s_nop 0
	s_nop 0
	s_nop 0
	ds_read_b128 v[116:119], v52 offset:18496
	s_nop 0
	s_waitcnt lgkmcnt(7)
	v_mfma_f32_16x16x32_bf16 v[4:7], v[168:171], v[172:175], 0
	s_nop 0
	s_waitcnt lgkmcnt(6)
	v_mfma_f32_16x16x32_bf16 v[0:3], v[168:171], v[176:179], 0
	s_nop 0
	s_nop 0
	s_waitcnt lgkmcnt(0)
	v_mfma_f32_16x16x32_bf16 v[4:7], v[116:119], v[180:183], v[4:7]
	ds_read_b128 v[18:21], v53 offset:30016
	s_nop 0
	s_waitcnt lgkmcnt(0)
	v_mfma_f32_16x16x32_bf16 v[0:3], v[116:119], v[18:21], v[0:3]
	s_nop 4
	v_cndmask_b32_e64 v4, v4, 0, s[66:67]
	v_cndmask_b32_e64 v5, 0, v5, s[54:55]
	v_cndmask_b32_e64 v6, v6, 0, s[72:73]
	v_cndmask_b32_e64 v7, v7, 0, s[16:17]
	v_cndmask_b32_e64 v18, 0, v0, s[76:77]
	v_cndmask_b32_e64 v19, 0, v1, s[78:79]
	v_cndmask_b32_e64 v2, 0, v2, s[80:81]
	v_cndmask_b32_e64 v3, 0, v3, s[82:83]
	v_cvt_pk_bf16_f32 v0, v4, v5
	v_cvt_pk_bf16_f32 v1, v6, v7
	ds_write_b64 v85, v[0:1]
	v_cvt_pk_bf16_f32 v0, v18, v19
	v_cvt_pk_bf16_f32 v1, v2, v3
	s_waitcnt lgkmcnt(0)
	ds_write_b64 v86, v[0:1]
	s_waitcnt lgkmcnt(0)
	s_barrier
	ds_read_b128 v[0:3], v52 offset:64512
	ds_read_b128 v[4:7], v53 offset:55296
	ds_read_b128 v[18:21], v53 offset:57600
	ds_read_b128 v[116:119], v52 offset:64576
	s_waitcnt lgkmcnt(2)
	v_mfma_f32_16x16x32_bf16 v[4:7], v[0:3], v[4:7], 0
	s_waitcnt lgkmcnt(1)
	v_mfma_f32_16x16x32_bf16 v[0:3], v[0:3], v[18:21], 0
	ds_read_b128 v[18:21], v53 offset:55360
	s_waitcnt lgkmcnt(0)
	v_mfma_f32_16x16x32_bf16 v[4:7], v[116:119], v[18:21], v[4:7]
	ds_read_b128 v[18:21], v53 offset:57664
	s_waitcnt lgkmcnt(0)
	v_mfma_f32_16x16x32_bf16 v[0:3], v[116:119], v[18:21], v[0:3]
	s_nop 4
	v_cvt_pk_bf16_f32 v4, v4, v5
	v_cvt_pk_bf16_f32 v5, v6, v7
	ds_write_b64 v57, v[4:5]
	v_cvt_pk_bf16_f32 v0, v0, v1
	v_cvt_pk_bf16_f32 v1, v2, v3
	ds_write_b64 v57, v[0:1] offset:2304
	s_cbranch_vccnz .LBB0_428
; __device__ __forceinline__ unsigned f2bf(float f) { return pk2(f, f) & 0xffffu; }
; __device__ __forceinline__ void chunk_item(const PAArgs& A, unsigned char* lds, int item, int tid, int wave, int lane, const ChunkRaw& RAW) {
;     ...
;         if (wave == 0) {
;             const int bi = lane >> 4, cc = lane & 15;
;             float t[16];
; #pragma unroll
;             for (int r = 0; r < 16; ++r) {
;                 float acc = (r == cc) ? 1.f : 0.f;
; #pragma unroll
;                 for (int k = 0; k < r; ++k) acc += Dg[(bi * 16 + r) * 16 + k] * t[k];
;                 t[r] = acc;
;             }
; #pragma unroll
;             for (int r = 0; r < 16; ++r) Tinv[(bi * 16 + r) * TST + cc] = (bf16)f2bf(t[r]);
;         }
	ds_write_b16 v95, v87
	ds_read_b32 v116, v58 offset:64
	ds_read_b64 v[120:121], v58 offset:128
	ds_read_b96 v[124:126], v58 offset:192
	ds_read_b128 v[128:131], v58 offset:256
	ds_read_b128 v[132:135], v58 offset:320
	ds_read_b32 v136, v58 offset:336
	ds_read_b128 v[140:143], v58 offset:384
	ds_read_b64 v[144:145], v58 offset:400
	ds_read_b128 v[148:151], v58 offset:448
	ds_read_b96 v[152:154], v58 offset:464
	ds_read_b128 v[156:159], v58 offset:512
	ds_read_b128 v[160:163], v58 offset:528
	ds_read_b128 v[164:167], v58 offset:576
	ds_read_b128 v[168:171], v58 offset:592
	ds_read_b32 v172, v58 offset:608
	ds_read_b128 v[176:179], v58 offset:640
	ds_read_b128 v[180:183], v58 offset:656
	ds_read_b64 v[184:185], v58 offset:672
	ds_read_b128 v[188:191], v58 offset:704
	ds_read_b128 v[192:195], v58 offset:720
	ds_read_b96 v[196:198], v58 offset:736
	ds_read_b128 v[200:203], v58 offset:768
	ds_read_b128 v[204:207], v58 offset:784
	ds_read_b128 v[208:211], v58 offset:800
	ds_read_b128 v[212:215], v58 offset:832
	ds_read_b128 v[216:219], v58 offset:848
	ds_read_b128 v[220:223], v58 offset:864
	ds_read_b32 v224, v58 offset:880
	ds_read_b128 v[226:229], v58 offset:896
	ds_read_b128 v[230:233], v58 offset:912
	ds_read_b128 v[234:237], v58 offset:928
	ds_read_b64 v[238:239], v58 offset:944
	s_waitcnt lgkmcnt(15)
	v_fma_f32 v0, v54, v116, v55
	s_waitcnt lgkmcnt(15)
	v_fma_f32 v1, v54, v120, v59
	v_fmac_f32_e32 v1, v0, v121
	s_waitcnt lgkmcnt(15)
	v_fma_f32 v2, v54, v124, v60
	v_fmac_f32_e32 v2, v0, v125
	v_fmac_f32_e32 v2, v1, v126
	s_waitcnt lgkmcnt(15)
	v_fma_f32 v3, v54, v128, v61
	v_fmac_f32_e32 v3, v0, v129
	v_fmac_f32_e32 v3, v1, v130
	v_fmac_f32_e32 v3, v2, v131
	s_waitcnt lgkmcnt(15)
	v_fma_f32 v4, v54, v132, v62
	v_fmac_f32_e32 v4, v0, v133
	v_fmac_f32_e32 v4, v1, v134
	v_fmac_f32_e32 v4, v2, v135
	v_fmac_f32_e32 v4, v3, v136
	s_waitcnt lgkmcnt(15)
	v_fma_f32 v5, v54, v140, v63
	v_fmac_f32_e32 v5, v0, v141
	v_fmac_f32_e32 v5, v1, v142
	v_fmac_f32_e32 v5, v2, v143
	v_fmac_f32_e32 v5, v3, v144
	v_fmac_f32_e32 v5, v4, v145
	s_waitcnt lgkmcnt(15)
	v_fma_f32 v6, v54, v148, v64
	v_fmac_f32_e32 v6, v0, v149
	v_fmac_f32_e32 v6, v1, v150
	v_fmac_f32_e32 v6, v2, v151
	v_fmac_f32_e32 v6, v3, v152
	v_fmac_f32_e32 v6, v4, v153
	v_fmac_f32_e32 v6, v5, v154
	s_waitcnt lgkmcnt(15)
	v_fma_f32 v7, v54, v156, v65
	v_fmac_f32_e32 v7, v0, v157
	v_fmac_f32_e32 v7, v1, v158
	v_fmac_f32_e32 v7, v2, v159
	v_fmac_f32_e32 v7, v3, v160
	v_fmac_f32_e32 v7, v4, v161
	v_fmac_f32_e32 v7, v5, v162
	v_fmac_f32_e32 v7, v6, v163
	s_waitcnt lgkmcnt(15)
	v_fma_f32 v18, v54, v164, v66
	v_fmac_f32_e32 v18, v0, v165
	v_fmac_f32_e32 v18, v1, v166
	v_fmac_f32_e32 v18, v2, v167
	v_fmac_f32_e32 v18, v3, v168
	v_fmac_f32_e32 v18, v4, v169
	v_fmac_f32_e32 v18, v5, v170
	v_fmac_f32_e32 v18, v6, v171
	v_fmac_f32_e32 v18, v7, v172
	s_waitcnt lgkmcnt(14)
	v_fma_f32 v19, v54, v176, v67
	v_fmac_f32_e32 v19, v0, v177
	v_fmac_f32_e32 v19, v1, v178
	v_fmac_f32_e32 v19, v2, v179
	v_fmac_f32_e32 v19, v3, v180
	v_fmac_f32_e32 v19, v4, v181
	v_fmac_f32_e32 v19, v5, v182
	v_fmac_f32_e32 v19, v6, v183
	v_fmac_f32_e32 v19, v7, v184
	v_fmac_f32_e32 v19, v18, v185
	ds_read_b128 v[116:119], v58 offset:960
	ds_read_b128 v[120:123], v58 offset:976
	ds_read_b128 v[124:127], v58 offset:992
	ds_read_b96 v[128:130], v58 offset:1008
	s_waitcnt lgkmcnt(15)
	v_fma_f32 v20, v54, v188, v68
	v_fmac_f32_e32 v20, v0, v189
	v_fmac_f32_e32 v20, v1, v190
	v_fmac_f32_e32 v20, v2, v191
	v_fmac_f32_e32 v20, v3, v192
	v_fmac_f32_e32 v20, v4, v193
	v_fmac_f32_e32 v20, v5, v194
	v_fmac_f32_e32 v20, v6, v195
	v_fmac_f32_e32 v20, v7, v196
	v_fmac_f32_e32 v20, v18, v197
	v_fmac_f32_e32 v20, v19, v198
	s_waitcnt lgkmcnt(12)
	v_fma_f32 v21, v54, v200, v69
	v_fmac_f32_e32 v21, v0, v201
	v_fmac_f32_e32 v21, v1, v202
	v_fmac_f32_e32 v21, v2, v203
	v_fmac_f32_e32 v21, v3, v204
	v_fmac_f32_e32 v21, v4, v205
	v_fmac_f32_e32 v21, v5, v206
	v_fmac_f32_e32 v21, v6, v207
	v_fmac_f32_e32 v21, v7, v208
	v_fmac_f32_e32 v21, v18, v209
	v_fmac_f32_e32 v21, v19, v210
	v_fmac_f32_e32 v21, v20, v211
	s_waitcnt lgkmcnt(8)
	v_fma_f32 v115, v54, v212, v70
	v_fmac_f32_e32 v115, v0, v213
	v_fmac_f32_e32 v115, v1, v214
	v_fmac_f32_e32 v115, v2, v215
	v_fmac_f32_e32 v115, v3, v216
	v_fmac_f32_e32 v115, v4, v217
	v_fmac_f32_e32 v115, v5, v218
	v_fmac_f32_e32 v115, v6, v219
	v_fmac_f32_e32 v115, v7, v220
	v_fmac_f32_e32 v115, v18, v221
	v_fmac_f32_e32 v115, v19, v222
	v_fmac_f32_e32 v115, v20, v223
	v_fmac_f32_e32 v115, v21, v224
	s_waitcnt lgkmcnt(4)
	v_fma_f32 v132, v54, v226, v71
	v_fmac_f32_e32 v132, v0, v227
	v_fmac_f32_e32 v132, v1, v228
	v_fmac_f32_e32 v132, v2, v229
	v_fmac_f32_e32 v132, v3, v230
	v_fmac_f32_e32 v132, v4, v231
	v_fmac_f32_e32 v132, v5, v232
	v_fmac_f32_e32 v132, v6, v233
	v_fmac_f32_e32 v132, v7, v234
	v_fmac_f32_e32 v132, v18, v235
	v_fmac_f32_e32 v132, v19, v236
	v_fmac_f32_e32 v132, v20, v237
	v_fmac_f32_e32 v132, v21, v238
	v_fmac_f32_e32 v132, v115, v239
	s_waitcnt lgkmcnt(0)
	v_fma_f32 v133, v54, v116, v72
	v_fmac_f32_e32 v133, v0, v117
	v_fmac_f32_e32 v133, v1, v118
	v_fmac_f32_e32 v133, v2, v119
	v_fmac_f32_e32 v133, v3, v120
	v_fmac_f32_e32 v133, v4, v121
	v_fmac_f32_e32 v133, v5, v122
	v_fmac_f32_e32 v133, v6, v123
	v_fmac_f32_e32 v133, v7, v124
	v_fmac_f32_e32 v133, v18, v125
	v_fmac_f32_e32 v133, v19, v126
	v_fmac_f32_e32 v133, v20, v127
	v_fmac_f32_e32 v133, v21, v128
	v_fmac_f32_e32 v133, v115, v129
	v_fmac_f32_e32 v133, v132, v130
	v_cvt_pk_bf16_f32 v135, v0, s0
	ds_write_b16 v95, v135 offset:40
	v_cvt_pk_bf16_f32 v134, v1, s0
	ds_write_b16 v95, v134 offset:80
	v_cvt_pk_bf16_f32 v135, v2, s0
	ds_write_b16 v95, v135 offset:120
	v_cvt_pk_bf16_f32 v134, v3, s0
	ds_write_b16 v95, v134 offset:160
	v_cvt_pk_bf16_f32 v135, v4, s0
	ds_write_b16 v95, v135 offset:200
	v_cvt_pk_bf16_f32 v134, v5, s0
	ds_write_b16 v95, v134 offset:240
	v_cvt_pk_bf16_f32 v135, v6, s0
	ds_write_b16 v95, v135 offset:280
	v_cvt_pk_bf16_f32 v134, v7, s0
	ds_write_b16 v95, v134 offset:320
	v_cvt_pk_bf16_f32 v135, v18, s0
	ds_write_b16 v95, v135 offset:360
	v_cvt_pk_bf16_f32 v134, v19, s0
	ds_write_b16 v95, v134 offset:400
	v_cvt_pk_bf16_f32 v135, v20, s0
	ds_write_b16 v95, v135 offset:440
	v_cvt_pk_bf16_f32 v134, v21, s0
	ds_write_b16 v95, v134 offset:480
	v_cvt_pk_bf16_f32 v135, v115, s0
	ds_write_b16 v95, v135 offset:520
	v_cvt_pk_bf16_f32 v134, v132, s0
	ds_write_b16 v95, v134 offset:560
	v_cvt_pk_bf16_f32 v135, v133, s0
	ds_write_b16 v96, v135
	s_branch .LBB0_428
